# attention (prompt): V tile loaded row-contiguous like K (8 cache lines per wave-load instead of 64) and re-mapped to the key-per-lane layout through an LDS bounce buffer before the transposed staging
# speedup vs baseline: 1.0165x; 1.0165x over previous
; #define LAS __attribute__((address_space(3)))
; __device__ __forceinline__ void attn_item(const Params& P, int l, LAS unsigned char* lds, int item, const int wv) {
;     ...
;     for (int jt = 0; jt < nkt; ++jt) {
;         __syncthreads();
; #pragma unroll
;         for (int i = 0; i < 4; ++i) {
;             { const int idx = tid + 512 * i, key = idx >> 5, hc = idx & 31, hh = hc >> 4, ch = hc & 15;
;               *(LAS u32x4*)(Kl + (hh * 64 + key) * 136 + 8 * ch) = kreg[i]; }
;             { const int idx = tid + 512 * i, key = idx & 63, hc = idx >> 6, hh = hc >> 4, ch = hc & 15; const u32x4 vv = vreg[i];
;               LAS bf16_t* d = Vt + (hh * 128 + 8 * ch) * 72 + key;
;               d[0 * 72] = (bf16_t)(vv.x & 0xffffu); d[1 * 72] = (bf16_t)(vv.x >> 16); d[2 * 72] = (bf16_t)(vv.y & 0xffffu); d[3 * 72] = (bf16_t)(vv.y >> 16);
;               d[4 * 72] = (bf16_t)(vv.z & 0xffffu); d[5 * 72] = (bf16_t)(vv.z >> 16); d[6 * 72] = (bf16_t)(vv.w & 0xffffu); d[7 * 72] = (bf16_t)(vv.w >> 16); }
;         }
;         if (jt + 1 < nkt) ATT_LOAD(jt + 1);
.LBB0_352:
	s_and_b64 vcc, exec, s[38:39]
	s_cbranch_vccnz .Lattn_nobounce
	v_and_b32_e32 v82, 31, v114
	v_mul_u32_u24_e32 v83, 0x210, v102
	v_lshl_add_u32 v82, v82, 4, v83
	v_add_u32_e32 v82, 0x12800, v82
	v_mul_u32_u24_e32 v84, 0x210, v114
	v_lshrrev_b32_e32 v85, 1, v102
	v_lshl_add_u32 v84, v85, 4, v84
	v_add_u32_e32 v84, 0x12800, v84
	s_waitcnt vmcnt(0)
	ds_write_b128 v82, v[22:25]
	ds_write_b128 v82, v[30:33] offset:8448
	ds_write_b128 v82, v[38:41] offset:16896
	ds_write_b128 v82, v[46:49] offset:25344
	s_waitcnt lgkmcnt(0)
	s_barrier
	ds_read_b128 v[22:25], v84
	ds_read_b128 v[30:33], v84 offset:128
	ds_read_b128 v[38:41], v84 offset:256
	ds_read_b128 v[46:49], v84 offset:384
	s_waitcnt lgkmcnt(0)
.Lattn_nobounce:
	s_add_i32 s20, s21, 1
	s_cmp_ge_i32 s20, s25
	s_waitcnt lgkmcnt(0)
	s_barrier
	s_waitcnt vmcnt(7)
	ds_write_b128 v165, v[18:21]
	s_waitcnt vmcnt(6)
	ds_write_b16 v166, v22 offset:34816
	ds_write_b16_d16_hi v166, v22 offset:34960
	ds_write_b16 v166, v23 offset:35104
	ds_write_b16_d16_hi v166, v23 offset:35248
	ds_write_b16 v166, v24 offset:35392
	ds_write_b16_d16_hi v166, v24 offset:35536
	ds_write_b16 v166, v25 offset:35680
	ds_write_b16_d16_hi v166, v25 offset:35824
	s_waitcnt vmcnt(5)
	ds_write_b128 v167, v[26:29]
	s_waitcnt vmcnt(4)
	ds_write_b16 v168, v30 offset:34816
	ds_write_b16_d16_hi v168, v30 offset:34960
	ds_write_b16 v168, v31 offset:35104
	ds_write_b16_d16_hi v168, v31 offset:35248
	ds_write_b16 v168, v32 offset:35392
	ds_write_b16_d16_hi v168, v32 offset:35536
	ds_write_b16 v168, v33 offset:35680
	ds_write_b16_d16_hi v168, v33 offset:35824
	s_waitcnt vmcnt(3)
	ds_write_b128 v169, v[34:37]
	s_waitcnt vmcnt(2)
	ds_write_b16 v170, v38 offset:34816
	ds_write_b16_d16_hi v170, v38 offset:34960
	ds_write_b16 v170, v39 offset:35104
	ds_write_b16_d16_hi v170, v39 offset:35248
	ds_write_b16 v170, v40 offset:35392
	ds_write_b16_d16_hi v170, v40 offset:35536
	ds_write_b16 v170, v41 offset:35680
	ds_write_b16_d16_hi v170, v41 offset:35824
	s_waitcnt vmcnt(0)
	ds_write_b128 v171, v[42:45]
	s_waitcnt vmcnt(0)
	ds_write_b16 v172, v46 offset:34816
	ds_write_b16_d16_hi v172, v46 offset:34960
	ds_write_b16 v172, v47 offset:35104
	ds_write_b16_d16_hi v172, v47 offset:35248
	ds_write_b16 v172, v48 offset:35392
	ds_write_b16_d16_hi v172, v48 offset:35536
	ds_write_b16 v172, v49 offset:35680
	ds_write_b16_d16_hi v172, v49 offset:35824
	s_cbranch_scc1 .LBB0_376
	s_and_b64 vcc, exec, s[38:39]
	s_mov_b64 s[14:15], -1
	s_cbranch_vccnz .LBB0_355
	v_add_u32_e32 v20, s19, v164
	v_mov_b64_e32 v[18:19], s[30:31]
	v_mad_u64_u32 v[18:19], s[14:15], v20, s13, v[18:19]
	v_lshl_add_u64 v[18:19], v[18:19], 0, s[82:83]
	s_mov_b64 s[14:15], 0x1000
	v_lshl_add_u64 v[42:43], v[18:19], 0, s[14:15]
	v_add_u32_e32 v18, s19, v163
	v_add_u32_e32 v26, s19, v162
	v_add_u32_e32 v34, s19, v161
	v_add_u32_e32 v44, s19, v160
	v_mad_i64_i32 v[18:19], s[14:15], v18, s13, v[140:141]
	v_lshl_add_u64 v[22:23], v[104:105], 1, v[42:43]
	v_mad_i64_i32 v[26:27], s[14:15], v26, s13, v[140:141]
	v_lshl_add_u64 v[30:31], v[116:117], 1, v[42:43]
	v_mad_i64_i32 v[34:35], s[14:15], v34, s13, v[140:141]
	v_lshl_add_u64 v[38:39], v[118:119], 1, v[42:43]
	v_mad_i64_i32 v[44:45], s[14:15], v44, s13, v[140:141]
	v_lshl_add_u64 v[46:47], v[120:121], 1, v[42:43]
	s_mov_b64 s[14:15], 0x1000
	v_lshl_add_u64 v[22:23], v[18:19], 0, s[14:15]
	v_lshl_add_u64 v[30:31], v[26:27], 0, s[14:15]
	v_lshl_add_u64 v[38:39], v[34:35], 0, s[14:15]
	v_lshl_add_u64 v[46:47], v[44:45], 0, s[14:15]
	global_load_dwordx4 v[18:21], v[18:19], off offset:2048
	s_nop 0
	global_load_dwordx4 v[22:25], v[22:23], off
	s_nop 0
	global_load_dwordx4 v[26:29], v[26:27], off offset:2048
	s_nop 0
	global_load_dwordx4 v[30:33], v[30:31], off
	s_nop 0
	global_load_dwordx4 v[34:37], v[34:35], off offset:2048
	s_nop 0
	global_load_dwordx4 v[38:41], v[38:39], off
	s_nop 0
	global_load_dwordx4 v[42:45], v[44:45], off offset:2048
	s_nop 0
	global_load_dwordx4 v[46:49], v[46:47], off
	s_mov_b64 s[14:15], 0

; __device__ __forceinline__ void attn_item(const Params& P, int l, LAS unsigned char* lds, int item, const int wv) {
;     ...
;     ATT_LOAD(0);
.LBB0_390:
	v_and_or_b32 v8, v50, 63, s34
	v_mov_b64_e32 v[42:43], s[30:31]
	v_mad_u64_u32 v[18:19], s[8:9], v8, s13, v[42:43]
	s_lshl_b32 s82, s28, 8
	v_lshl_add_u64 v[18:19], v[18:19], 0, s[82:83]
	s_mov_b64 s[8:9], 0x1000
	v_add_u32_e32 v8, s34, v102
	v_add_u32_e32 v26, s34, v106
	v_add_u32_e32 v34, s34, v108
	v_add_u32_e32 v46, s34, v110
	v_lshl_add_u64 v[44:45], v[18:19], 0, s[8:9]
	v_mad_i64_i32 v[18:19], s[8:9], v8, s13, v[42:43]
	v_mad_i64_i32 v[26:27], s[8:9], v26, s13, v[42:43]
	v_and_b32_e32 v28, -8, v57
	v_mad_i64_i32 v[34:35], s[8:9], v34, s13, v[42:43]
	v_and_b32_e32 v36, -8, v56
	v_mad_i64_i32 v[42:43], s[8:9], v46, s13, v[42:43]
	v_and_b32_e32 v46, -8, v55
	v_lshl_add_u64 v[18:19], v[18:19], 0, s[82:83]
	v_and_b32_e32 v8, 0x1f0, v61
	v_ashrrev_i32_e32 v105, 31, v104
	v_lshl_add_u64 v[26:27], v[26:27], 0, s[82:83]
	v_ashrrev_i32_e32 v29, 31, v28
	v_lshl_add_u64 v[34:35], v[34:35], 0, s[82:83]
	v_ashrrev_i32_e32 v37, 31, v36
	v_lshl_add_u64 v[42:43], v[42:43], 0, s[82:83]
	v_ashrrev_i32_e32 v47, 31, v46
	v_lshl_add_u64 v[18:19], v[18:19], 0, v[8:9]
	v_lshl_add_u64 v[22:23], v[104:105], 1, v[44:45]
	v_lshl_add_u64 v[26:27], v[26:27], 0, v[8:9]
	v_lshl_add_u64 v[30:31], v[28:29], 1, v[44:45]
	v_lshl_add_u64 v[34:35], v[34:35], 0, v[8:9]
	v_lshl_add_u64 v[38:39], v[36:37], 1, v[44:45]
	v_lshl_add_u64 v[42:43], v[42:43], 0, v[8:9]
	v_lshl_add_u64 v[46:47], v[46:47], 1, v[44:45]
	s_mov_b64 s[8:9], 0x1000
	v_lshl_add_u64 v[22:23], v[18:19], 0, s[8:9]
	v_lshl_add_u64 v[30:31], v[26:27], 0, s[8:9]
	v_lshl_add_u64 v[38:39], v[34:35], 0, s[8:9]
	v_lshl_add_u64 v[46:47], v[42:43], 0, s[8:9]
	global_load_dwordx4 v[18:21], v[18:19], off offset:2048
	s_nop 0
	global_load_dwordx4 v[22:25], v[22:23], off
	s_nop 0
	global_load_dwordx4 v[26:29], v[26:27], off offset:2048
	s_nop 0
	global_load_dwordx4 v[30:33], v[30:31], off
	s_nop 0
	global_load_dwordx4 v[34:37], v[34:35], off offset:2048
	s_nop 0
	global_load_dwordx4 v[38:41], v[38:39], off
	s_nop 0
	global_load_dwordx4 v[42:45], v[42:43], off offset:2048
	s_nop 0
	global_load_dwordx4 v[46:49], v[46:47], off
	v_ashrrev_i32_e32 v103, 31, v102
	s_cbranch_execnz .LBB0_350
